# in-proj gate columns as one 32x16 fragment-loaded mini tile per workgroup (4-way k split summed in fixed order through LDS) instead of 128 extra 128x128 tiles
# speedup vs baseline: 1.0126x; 1.0030x over previous
; __global__ void __launch_bounds__(256, 2) hymba_mega(Params p) {
;     ...
;     for (int tile = blockIdx.x; tile < 2048 + 128; tile += gridDim.x) {
;       if (tile < 2048) {
.LBB0_220:
	s_add_i32 s61, s61, s88
	s_add_i32 s6, s6, s0
	s_add_i32 s1, s1, s3
	s_cmpk_gt_i32 s61, 0x7ff
	s_cbranch_scc1 .Lgm_start

; DI void xcd_barrier(const XcdBarrier& b) {
;   asm volatile("s_waitcnt vmcnt(0)" ::: "memory");
;   __syncthreads();
;   if (threadIdx.x == 0) {
;     unsigned* bar = b.bar;
;     __builtin_amdgcn_s_waitcnt(0);
;     unsigned nloc = b.st[0], nx = b.st[1];
;     if (nloc == 0u) { xcd_barrier_complete(bar, b.x, nloc, nx); b.st[0] = nloc; b.st[1] = nx; }
; __global__ void __launch_bounds__(256, 2) hymba_mega(Params p) {
;     ...
;       } else {
;         const int mt = tile - 2048;
;         gemm128((const bf16_t*)p.out, 1024, (const bf16_t*)(ws + OFF_WINT), 1024, 1024, mt * 128, 4096, sA, sB,
;                 [&](int m, int n, float v) { if (n < 4112) G[(size_t)(n - 4096) * T_TOK + m] = v; });
;       }
.Lgm_start:
	v_readlane_b32 s98, v230, 8
	v_lshrrev_b32_e32 v4, 6, v192
	v_and_b32_e32 v5, 15, v192
	v_bfe_u32 v6, v192, 4, 2
	s_nop 0
	v_readfirstlane_b32 s99, v4
	s_lshl_b32 s4, s98, 5
	v_add_u32_e32 v7, s4, v5
	v_lshlrev_b32_e32 v7, 11, v7
	s_lshl_b32 s5, s99, 9
	v_lshl_add_u32 v8, v6, 4, s5
	v_add_u32_e32 v9, v7, v8
	v_add_u32_e32 v10, 0x8000, v9
	v_lshl_add_u32 v11, v5, 11, v8
	s_add_u32 s100, s86, 0xd000000
	s_addc_u32 s101, s87, 0
	global_load_dwordx4 v[80:83], v11, s[100:101] offset:0
	global_load_dwordx4 v[16:19], v9, s[84:85] offset:0
	global_load_dwordx4 v[48:51], v10, s[84:85] offset:0
	global_load_dwordx4 v[84:87], v11, s[100:101] offset:64
	global_load_dwordx4 v[20:23], v9, s[84:85] offset:64
	global_load_dwordx4 v[52:55], v10, s[84:85] offset:64
	global_load_dwordx4 v[88:91], v11, s[100:101] offset:128
	global_load_dwordx4 v[24:27], v9, s[84:85] offset:128
	global_load_dwordx4 v[56:59], v10, s[84:85] offset:128
	global_load_dwordx4 v[92:95], v11, s[100:101] offset:192
	global_load_dwordx4 v[28:31], v9, s[84:85] offset:192
	global_load_dwordx4 v[60:63], v10, s[84:85] offset:192
	global_load_dwordx4 v[96:99], v11, s[100:101] offset:256
	global_load_dwordx4 v[32:35], v9, s[84:85] offset:256
	global_load_dwordx4 v[64:67], v10, s[84:85] offset:256
	global_load_dwordx4 v[100:103], v11, s[100:101] offset:320
	global_load_dwordx4 v[36:39], v9, s[84:85] offset:320
	global_load_dwordx4 v[68:71], v10, s[84:85] offset:320
	global_load_dwordx4 v[104:107], v11, s[100:101] offset:384
	global_load_dwordx4 v[40:43], v9, s[84:85] offset:384
	global_load_dwordx4 v[72:75], v10, s[84:85] offset:384
	global_load_dwordx4 v[108:111], v11, s[100:101] offset:448
	global_load_dwordx4 v[44:47], v9, s[84:85] offset:448
	global_load_dwordx4 v[76:79], v10, s[84:85] offset:448
	s_waitcnt vmcnt(22)
	v_mfma_f32_16x16x32_bf16 v[112:115], v[16:19], v[80:83], 0
	s_waitcnt vmcnt(21)
	v_mfma_f32_16x16x32_bf16 v[116:119], v[48:51], v[80:83], 0
	s_waitcnt vmcnt(19)
	v_mfma_f32_16x16x32_bf16 v[112:115], v[20:23], v[84:87], v[112:115]
	s_waitcnt vmcnt(18)
	v_mfma_f32_16x16x32_bf16 v[116:119], v[52:55], v[84:87], v[116:119]
	s_waitcnt vmcnt(16)
	v_mfma_f32_16x16x32_bf16 v[112:115], v[24:27], v[88:91], v[112:115]
	s_waitcnt vmcnt(15)
	v_mfma_f32_16x16x32_bf16 v[116:119], v[56:59], v[88:91], v[116:119]
	s_waitcnt vmcnt(13)
	v_mfma_f32_16x16x32_bf16 v[112:115], v[28:31], v[92:95], v[112:115]
	s_waitcnt vmcnt(12)
	v_mfma_f32_16x16x32_bf16 v[116:119], v[60:63], v[92:95], v[116:119]
	s_waitcnt vmcnt(10)
	v_mfma_f32_16x16x32_bf16 v[112:115], v[32:35], v[96:99], v[112:115]
	s_waitcnt vmcnt(9)
	v_mfma_f32_16x16x32_bf16 v[116:119], v[64:67], v[96:99], v[116:119]
	s_waitcnt vmcnt(7)
	v_mfma_f32_16x16x32_bf16 v[112:115], v[36:39], v[100:103], v[112:115]
	s_waitcnt vmcnt(6)
	v_mfma_f32_16x16x32_bf16 v[116:119], v[68:71], v[100:103], v[116:119]
	s_waitcnt vmcnt(4)
	v_mfma_f32_16x16x32_bf16 v[112:115], v[40:43], v[104:107], v[112:115]
	s_waitcnt vmcnt(3)
	v_mfma_f32_16x16x32_bf16 v[116:119], v[72:75], v[104:107], v[116:119]
	s_waitcnt vmcnt(1)
	v_mfma_f32_16x16x32_bf16 v[112:115], v[44:47], v[108:111], v[112:115]
	s_waitcnt vmcnt(0)
	v_mfma_f32_16x16x32_bf16 v[116:119], v[76:79], v[108:111], v[116:119]
	v_and_b32_e32 v12, 63, v192
	v_lshlrev_b32_e32 v12, 4, v12
	s_lshl_b32 s5, s99, 11
	v_add_u32_e32 v13, s5, v12
	s_barrier
	s_nop 7
	s_nop 7
	ds_write_b128 v13, v[112:115]
	ds_write_b128 v13, v[116:119] offset:1024
	s_waitcnt lgkmcnt(0)
	s_barrier
	s_cmp_gt_u32 s99, 1
	s_cbranch_scc1 .Lgm_end
	s_lshl_b32 s5, s99, 10
	v_add_u32_e32 v13, s5, v12
	ds_read_b128 v[16:19], v13
	ds_read_b128 v[20:23], v13 offset:2048
	ds_read_b128 v[24:27], v13 offset:4096
	ds_read_b128 v[28:31], v13 offset:6144
	s_lshl_b32 s5, s99, 4
	s_add_i32 s5, s5, s4
	v_lshl_add_u32 v14, v6, 2, s5
	v_lshlrev_b32_e32 v14, 2, v14
	v_lshl_add_u32 v14, v5, 16, v14
	s_add_u32 s4, s86, 0xdec0000
	s_addc_u32 s5, s87, 0
	s_waitcnt lgkmcnt(2)
	v_pk_add_f32 v[16:17], v[16:17], v[20:21]
	v_pk_add_f32 v[18:19], v[18:19], v[22:23]
	s_waitcnt lgkmcnt(1)
	v_pk_add_f32 v[16:17], v[16:17], v[24:25]
	v_pk_add_f32 v[18:19], v[18:19], v[26:27]
	s_waitcnt lgkmcnt(0)
	v_pk_add_f32 v[16:17], v[16:17], v[28:29]
	v_pk_add_f32 v[18:19], v[18:19], v[30:31]
	s_nop 0
	global_store_dwordx4 v14, v[16:19], s[4:5]
.Lgm_end:
.LBB0_231:
	s_waitcnt vmcnt(0)
	s_waitcnt vmcnt(63) expcnt(7) lgkmcnt(15)
	s_barrier
	s_and_saveexec_b64 s[6:7], s[94:95]
	s_cbranch_execz .LBB0_283
	v_mov_b32_e32 v0, 0x13000
	s_waitcnt vmcnt(0) expcnt(0) lgkmcnt(0)
	ds_read_b32 v2, v0
	v_mov_b32_e32 v0, 0x13004
	ds_read_b32 v0, v0
	s_waitcnt lgkmcnt(1)
	v_cmp_ne_u32_e32 vcc, 0, v2
	s_cbranch_vccnz .LBB0_247
	s_add_u32 s8, s86, 0xe7c1200
	s_addc_u32 s9, s87, 0
	s_add_u32 s10, s86, 0xe7c1400
	s_addc_u32 s11, s87, 0
	s_add_u32 s12, s86, 0xe7c1500
	s_addc_u32 s13, s87, 0
	s_add_u32 s14, s86, 0xe7c1600
	s_addc_u32 s15, s87, 0
	s_add_u32 s16, s86, 0xe7c1700
	s_addc_u32 s17, s87, 0
	s_add_u32 s20, s86, 0xe7c1800
	s_addc_u32 s21, s87, 0
	s_add_u32 s34, s86, 0xe7c1900
	s_addc_u32 s35, s87, 0
	s_add_u32 s36, s86, 0xe7c1a00
	s_addc_u32 s37, s87, 0
	s_add_u32 s42, s86, 0xe7c1b00
	s_addc_u32 s43, s87, 0
	s_add_u32 s44, s86, 0xe7c1c00
	s_addc_u32 s45, s87, 0
	s_add_u32 s60, s86, 0xe7c1d00
	s_addc_u32 s61, s87, 0
	s_add_u32 s64, s86, 0xe7c1e00
	s_addc_u32 s65, s87, 0
	s_add_u32 s66, s86, 0xe7c1f00
	s_addc_u32 s67, s87, 0
	s_add_u32 s70, s86, 0xe7c2000
	s_addc_u32 s71, s87, 0
	s_add_u32 s72, s86, 0xe7c2100
	s_addc_u32 s73, s87, 0
	s_add_u32 s74, s86, 0xe7c2200
	s_addc_u32 s75, s87, 0
	s_mul_i32 s0, s89, s2
	s_add_u32 s92, s86, 0xe7c2300
	s_mul_i32 s0, s0, s88
	s_addc_u32 s93, s87, 0
	s_mov_b32 s1, 1
	v_mov_b32_e32 v16, 0
	s_branch .LBB0_235
